# grid-barrier and queue spin loops poll with s_sleep 0 instead of s_sleep 1
# speedup vs baseline: 1.0013x; 1.0013x over previous
; __device__ __forceinline__ unsigned xb_ld(unsigned* p)              { return __hip_atomic_load(p, __ATOMIC_RELAXED, __HIP_MEMORY_SCOPE_AGENT); }
; __device__ __forceinline__ void xcd_barrier_complete(unsigned* bar, unsigned x, unsigned& nloc, unsigned& nx) {
;     const unsigned G = gridDim.x * gridDim.y * gridDim.z;
;     unsigned sum, cnt, mine, sp = 0u;
;     for (;;) {
;         sum = 0u; cnt = 0u; mine = 0u;
; #pragma unroll
;         for (unsigned j = 0; j < 16; ++j) { const unsigned c = xb_ld(&bar[XB_XCNT(j)]); sum += c; cnt += (c > 0u) ? 1u : 0u; mine = (j == x) ? c : mine; }
;         if (sum == G) break;
;         __builtin_amdgcn_s_sleep(1);
;         if ((++sp & 255u) == 0u) { if (xb_ld(&bar[XB_TMO])) break; if (sp > XB_SPIN_CAP) { atomicAdd(&bar[XB_TMO], 1u); break; } }
;     }
.LBB0_248:
	global_load_dword v15, v16, s[8:9] sc1
	global_load_dword v0, v16, s[12:13] sc1
	global_load_dword v1, v16, s[14:15] sc1
	global_load_dword v2, v16, s[16:17] sc1
	global_load_dword v3, v16, s[18:19] sc1
	global_load_dword v4, v16, s[20:21] sc1
	global_load_dword v5, v16, s[22:23] sc1
	global_load_dword v6, v16, s[24:25] sc1
	global_load_dword v7, v16, s[26:27] sc1
	global_load_dword v8, v16, s[28:29] sc1
	global_load_dword v9, v16, s[30:31] sc1
	global_load_dword v10, v16, s[34:35] sc1
	global_load_dword v11, v16, s[36:37] sc1
	global_load_dword v12, v16, s[38:39] sc1
	global_load_dword v13, v16, s[40:41] sc1
	global_load_dword v14, v16, s[42:43] sc1
	s_mov_b64 s[44:45], -1
	s_mov_b64 s[46:47], -1
	s_waitcnt vmcnt(14)
	v_add_u32_e32 v17, v0, v15
	s_waitcnt vmcnt(13)
	v_add_u32_e32 v17, v17, v1
	s_waitcnt vmcnt(12)
	v_add_u32_e32 v17, v17, v2
	s_waitcnt vmcnt(11)
	v_add_u32_e32 v17, v17, v3
	s_waitcnt vmcnt(10)
	v_add_u32_e32 v17, v17, v4
	s_waitcnt vmcnt(9)
	v_add_u32_e32 v17, v17, v5
	s_waitcnt vmcnt(8)
	v_add_u32_e32 v17, v17, v6
	s_waitcnt vmcnt(7)
	v_add_u32_e32 v17, v17, v7
	s_waitcnt vmcnt(6)
	v_add_u32_e32 v17, v17, v8
	s_waitcnt vmcnt(5)
	v_add_u32_e32 v17, v17, v9
	s_waitcnt vmcnt(4)
	v_add_u32_e32 v17, v17, v10
	s_waitcnt vmcnt(3)
	v_add_u32_e32 v17, v17, v11
	s_waitcnt vmcnt(2)
	v_add_u32_e32 v17, v17, v12
	s_waitcnt vmcnt(1)
	v_add_u32_e32 v17, v17, v13
	s_waitcnt vmcnt(0)
	v_add_u32_e32 v17, v17, v14
	v_cmp_eq_u32_e32 vcc, s33, v17
	s_cbranch_vccnz .LBB0_247
	s_and_b32 s44, s50, 0xff
	s_cmp_eq_u32 s44, 0
	s_mov_b64 s[44:45], -1
	s_mov_b64 s[48:49], -1
	s_sleep 0
	s_cbranch_scc0 .LBB0_252
	global_load_dword v17, v16, s[6:7] sc1
	s_waitcnt vmcnt(0)
	v_cmp_eq_u32_e32 vcc, 0, v17
	s_cbranch_vccnz .LBB0_254
	s_mov_b64 s[48:49], 0

; __device__ __forceinline__ unsigned xb_ld(unsigned* p)              { return __hip_atomic_load(p, __ATOMIC_RELAXED, __HIP_MEMORY_SCOPE_AGENT); }
; __device__ __forceinline__ unsigned xb_add(unsigned* p, unsigned v) { return __hip_atomic_fetch_add(p, v, __ATOMIC_RELAXED, __HIP_MEMORY_SCOPE_AGENT); }
; #define XB_SPIN(cond, bar) do { unsigned _sp = 0; while (cond) { __builtin_amdgcn_s_sleep(1); \
;     if ((++_sp & 255u) == 0u) { if (xb_ld(&(bar)[XB_TMO])) break; if (_sp > XB_SPIN_CAP) { atomicAdd(&(bar)[XB_TMO], 1u); break; } } } } while (0)
; __device__ __forceinline__ void xcd_barrier(const XcdBarrier& b) {
;     ...
;             else XB_SPIN(xb_ld(&bar[XB_TOPGEN]) == tg, bar);
;             __builtin_amdgcn_fence(__ATOMIC_ACQUIRE, "agent");
;             xb_add(&bar[XB_XGEN(b.x)], 1u);
;             asm volatile("s_waitcnt vmcnt(0)" ::: "memory");
;         } else {
;             XB_SPIN(xb_ld(&bar[XB_XGEN(b.x)]) == gen, bar);
.LBB0_266:
	s_and_b32 s24, s28, 0xff
	s_mov_b64 s[22:23], -1
	s_cmp_lg_u32 s24, 0
	s_mov_b64 s[26:27], -1
	s_sleep 0
	s_cbranch_scc1 .LBB0_269
	global_load_dword v2, v0, s[14:15] sc1
	s_waitcnt vmcnt(0)
	v_cmp_eq_u32_e32 vcc, 0, v2
	s_cbranch_vccnz .LBB0_271
	s_mov_b64 s[26:27], 0
	s_mov_b64 s[24:25], -1

; __device__ __forceinline__ unsigned xb_ld(unsigned* p)              { return __hip_atomic_load(p, __ATOMIC_RELAXED, __HIP_MEMORY_SCOPE_AGENT); }
; __device__ __forceinline__ unsigned xb_add(unsigned* p, unsigned v) { return __hip_atomic_fetch_add(p, v, __ATOMIC_RELAXED, __HIP_MEMORY_SCOPE_AGENT); }
; #define XB_SPIN(cond, bar) do { unsigned _sp = 0; while (cond) { __builtin_amdgcn_s_sleep(1); \
;     if ((++_sp & 255u) == 0u) { if (xb_ld(&(bar)[XB_TMO])) break; if (_sp > XB_SPIN_CAP) { atomicAdd(&(bar)[XB_TMO], 1u); break; } } } } while (0)
; __device__ __forceinline__ void xcd_barrier(const XcdBarrier& b) {
;     ...
;             else XB_SPIN(xb_ld(&bar[XB_TOPGEN]) == tg, bar);
;             __builtin_amdgcn_fence(__ATOMIC_ACQUIRE, "agent");
;             xb_add(&bar[XB_XGEN(b.x)], 1u);
;             asm volatile("s_waitcnt vmcnt(0)" ::: "memory");
;         } else {
;             XB_SPIN(xb_ld(&bar[XB_XGEN(b.x)]) == gen, bar);
.LBB0_283:
	s_and_b32 s22, s28, 0xff
	s_cmp_lg_u32 s22, 0
	s_mov_b64 s[24:25], -1
	s_sleep 0
	s_cbranch_scc1 .LBB0_286
	global_load_dword v1, v0, s[14:15] sc1
	s_waitcnt vmcnt(0)
	v_cmp_eq_u32_e32 vcc, 0, v1
	s_cbranch_vccnz .LBB0_288
	s_mov_b64 s[24:25], 0
	s_mov_b64 s[22:23], -1

; __device__ __forceinline__ unsigned xb_ld(unsigned* p)              { return __hip_atomic_load(p, __ATOMIC_RELAXED, __HIP_MEMORY_SCOPE_AGENT); }
; __device__ __forceinline__ void xcd_barrier_complete(unsigned* bar, unsigned x, unsigned& nloc, unsigned& nx) {
;     const unsigned G = gridDim.x * gridDim.y * gridDim.z;
;     unsigned sum, cnt, mine, sp = 0u;
;     for (;;) {
;         sum = 0u; cnt = 0u; mine = 0u;
; #pragma unroll
;         for (unsigned j = 0; j < 16; ++j) { const unsigned c = xb_ld(&bar[XB_XCNT(j)]); sum += c; cnt += (c > 0u) ? 1u : 0u; mine = (j == x) ? c : mine; }
;         if (sum == G) break;
;         __builtin_amdgcn_s_sleep(1);
;         if ((++sp & 255u) == 0u) { if (xb_ld(&bar[XB_TMO])) break; if (sp > XB_SPIN_CAP) { atomicAdd(&bar[XB_TMO], 1u); break; } }
;     }
.LBB0_332:
	v_readlane_b32 s4, v254, 13
	v_readlane_b32 s5, v254, 14
	s_mov_b64 s[6:7], -1
	s_nop 3
	global_load_dword v0, v1, s[4:5] sc1
	v_readlane_b32 s4, v254, 15
	v_readlane_b32 s5, v254, 16
	s_nop 4
	global_load_dword v2, v1, s[4:5] sc1
	v_readlane_b32 s4, v254, 17
	v_readlane_b32 s5, v254, 18
	s_waitcnt vmcnt(0)
	v_add_u32_e32 v17, v2, v0
	s_nop 2
	global_load_dword v3, v1, s[4:5] sc1
	v_readlane_b32 s4, v254, 19
	v_readlane_b32 s5, v254, 20
	s_waitcnt vmcnt(0)
	v_add_u32_e32 v17, v17, v3
	s_nop 2
	global_load_dword v4, v1, s[4:5] sc1
	v_readlane_b32 s4, v254, 21
	v_readlane_b32 s5, v254, 22
	s_waitcnt vmcnt(0)
	v_add_u32_e32 v17, v17, v4
	s_nop 2
	global_load_dword v5, v1, s[4:5] sc1
	v_readlane_b32 s4, v254, 23
	v_readlane_b32 s5, v254, 24
	s_waitcnt vmcnt(0)
	v_add_u32_e32 v17, v17, v5
	s_nop 2
	global_load_dword v6, v1, s[4:5] sc1
	v_readlane_b32 s4, v254, 25
	v_readlane_b32 s5, v254, 26
	s_waitcnt vmcnt(0)
	v_add_u32_e32 v17, v17, v6
	s_nop 2
	global_load_dword v7, v1, s[4:5] sc1
	v_readlane_b32 s4, v254, 27
	v_readlane_b32 s5, v254, 28
	s_waitcnt vmcnt(0)
	v_add_u32_e32 v17, v17, v7
	s_nop 2
	global_load_dword v8, v1, s[4:5] sc1
	v_readlane_b32 s4, v254, 29
	v_readlane_b32 s5, v254, 30
	s_waitcnt vmcnt(0)
	v_add_u32_e32 v17, v17, v8
	s_nop 2
	global_load_dword v9, v1, s[4:5] sc1
	v_readlane_b32 s4, v254, 31
	v_readlane_b32 s5, v254, 32
	s_waitcnt vmcnt(0)
	v_add_u32_e32 v17, v17, v9
	s_nop 2
	global_load_dword v10, v1, s[4:5] sc1
	v_readlane_b32 s4, v254, 33
	v_readlane_b32 s5, v254, 34
	s_waitcnt vmcnt(0)
	v_add_u32_e32 v17, v17, v10
	s_nop 2
	global_load_dword v11, v1, s[4:5] sc1
	v_readlane_b32 s4, v254, 35
	v_readlane_b32 s5, v254, 36
	s_waitcnt vmcnt(0)
	v_add_u32_e32 v17, v17, v11
	s_nop 2
	global_load_dword v12, v1, s[4:5] sc1
	v_readlane_b32 s4, v254, 37
	v_readlane_b32 s5, v254, 38
	s_waitcnt vmcnt(0)
	v_add_u32_e32 v17, v17, v12
	s_nop 2
	global_load_dword v13, v1, s[4:5] sc1
	v_readlane_b32 s4, v254, 39
	v_readlane_b32 s5, v254, 40
	s_waitcnt vmcnt(0)
	v_add_u32_e32 v17, v17, v13
	s_nop 2
	global_load_dword v14, v1, s[4:5] sc1
	v_readlane_b32 s4, v254, 41
	v_readlane_b32 s5, v254, 42
	s_waitcnt vmcnt(0)
	v_add_u32_e32 v17, v17, v14
	s_nop 2
	global_load_dword v15, v1, s[4:5] sc1
	v_readlane_b32 s4, v254, 43
	v_readlane_b32 s5, v254, 44
	s_waitcnt vmcnt(0)
	v_add_u32_e32 v17, v17, v15
	s_nop 2
	global_load_dword v16, v1, s[4:5] sc1
	s_mov_b64 s[4:5], -1
	s_waitcnt vmcnt(0)
	v_add_u32_e32 v17, v17, v16
	v_cmp_eq_u32_e32 vcc, s8, v17
	s_cbranch_vccnz .LBB0_331
	s_and_b32 s4, s9, 0xff
	s_cmp_eq_u32 s4, 0
	s_mov_b64 s[4:5], -1
	s_mov_b64 s[38:39], -1
	s_sleep 0
	s_cbranch_scc0 .LBB0_336
	v_readlane_b32 s4, v254, 11
	v_readlane_b32 s5, v254, 12
	s_nop 4
	global_load_dword v17, v1, s[4:5] sc1
	s_waitcnt vmcnt(0)
	v_cmp_eq_u32_e32 vcc, 0, v17
	s_cbranch_vccnz .LBB0_338
	s_mov_b64 s[38:39], 0
	s_mov_b64 s[4:5], -1

; __device__ __forceinline__ unsigned xb_ld(unsigned* p)              { return __hip_atomic_load(p, __ATOMIC_RELAXED, __HIP_MEMORY_SCOPE_AGENT); }
; __device__ __forceinline__ unsigned xb_add(unsigned* p, unsigned v) { return __hip_atomic_fetch_add(p, v, __ATOMIC_RELAXED, __HIP_MEMORY_SCOPE_AGENT); }
; #define XB_SPIN(cond, bar) do { unsigned _sp = 0; while (cond) { __builtin_amdgcn_s_sleep(1); \
;     if ((++_sp & 255u) == 0u) { if (xb_ld(&(bar)[XB_TMO])) break; if (_sp > XB_SPIN_CAP) { atomicAdd(&(bar)[XB_TMO], 1u); break; } } } } while (0)
; __device__ __forceinline__ void xcd_barrier(const XcdBarrier& b) {
;     ...
;             else XB_SPIN(xb_ld(&bar[XB_TOPGEN]) == tg, bar);
;             __builtin_amdgcn_fence(__ATOMIC_ACQUIRE, "agent");
;             xb_add(&bar[XB_XGEN(b.x)], 1u);
;             asm volatile("s_waitcnt vmcnt(0)" ::: "memory");
;         } else {
;             XB_SPIN(xb_ld(&bar[XB_XGEN(b.x)]) == gen, bar);
.LBB0_352:
	s_and_b32 s9, s8, 0xff
	s_mov_b64 s[42:43], -1
	s_cmp_lg_u32 s9, 0
	s_mov_b64 s[48:49], -1
	s_sleep 0
	s_cbranch_scc1 .LBB0_355
	v_readlane_b32 s12, v254, 11
	v_readlane_b32 s13, v254, 12
	s_nop 4
	global_load_dword v2, v1, s[12:13] sc1
	s_waitcnt vmcnt(0)
	v_cmp_eq_u32_e32 vcc, 0, v2
	s_cbranch_vccnz .LBB0_357
	s_mov_b64 s[48:49], 0
	s_mov_b64 s[46:47], -1

; __device__ __forceinline__ unsigned xb_ld(unsigned* p)              { return __hip_atomic_load(p, __ATOMIC_RELAXED, __HIP_MEMORY_SCOPE_AGENT); }
; __device__ __forceinline__ unsigned xb_add(unsigned* p, unsigned v) { return __hip_atomic_fetch_add(p, v, __ATOMIC_RELAXED, __HIP_MEMORY_SCOPE_AGENT); }
; #define XB_SPIN(cond, bar) do { unsigned _sp = 0; while (cond) { __builtin_amdgcn_s_sleep(1); \
;     if ((++_sp & 255u) == 0u) { if (xb_ld(&(bar)[XB_TMO])) break; if (_sp > XB_SPIN_CAP) { atomicAdd(&(bar)[XB_TMO], 1u); break; } } } } while (0)
; __device__ __forceinline__ void xcd_barrier(const XcdBarrier& b) {
;     ...
;             else XB_SPIN(xb_ld(&bar[XB_TOPGEN]) == tg, bar);
;             __builtin_amdgcn_fence(__ATOMIC_ACQUIRE, "agent");
;             xb_add(&bar[XB_XGEN(b.x)], 1u);
;             asm volatile("s_waitcnt vmcnt(0)" ::: "memory");
;         } else {
;             XB_SPIN(xb_ld(&bar[XB_XGEN(b.x)]) == gen, bar);
.LBB0_544:
	s_and_b32 s9, s8, 0xff
	s_mov_b64 s[42:43], -1
	s_cmp_lg_u32 s9, 0
	s_mov_b64 s[46:47], -1
	s_sleep 0
	s_cbranch_scc1 .LBB0_547
	v_readlane_b32 s12, v254, 11
	v_readlane_b32 s13, v254, 12
	s_nop 4
	global_load_dword v2, v1, s[12:13] sc1
	s_waitcnt vmcnt(0)
	v_cmp_eq_u32_e32 vcc, 0, v2
	s_cbranch_vccnz .LBB0_549
	s_mov_b64 s[46:47], 0
	s_mov_b64 s[44:45], -1

; __device__ __forceinline__ unsigned xb_ld(unsigned* p)              { return __hip_atomic_load(p, __ATOMIC_RELAXED, __HIP_MEMORY_SCOPE_AGENT); }
; __device__ __forceinline__ unsigned xb_add(unsigned* p, unsigned v) { return __hip_atomic_fetch_add(p, v, __ATOMIC_RELAXED, __HIP_MEMORY_SCOPE_AGENT); }
; #define XB_SPIN(cond, bar) do { unsigned _sp = 0; while (cond) { __builtin_amdgcn_s_sleep(1); \
;     if ((++_sp & 255u) == 0u) { if (xb_ld(&(bar)[XB_TMO])) break; if (_sp > XB_SPIN_CAP) { atomicAdd(&(bar)[XB_TMO], 1u); break; } } } } while (0)
; __device__ __forceinline__ void xcd_barrier(const XcdBarrier& b) {
;     ...
;             else XB_SPIN(xb_ld(&bar[XB_TOPGEN]) == tg, bar);
;             __builtin_amdgcn_fence(__ATOMIC_ACQUIRE, "agent");
;             xb_add(&bar[XB_XGEN(b.x)], 1u);
;             asm volatile("s_waitcnt vmcnt(0)" ::: "memory");
;         } else {
;             XB_SPIN(xb_ld(&bar[XB_XGEN(b.x)]) == gen, bar);
.LBB0_707:
	s_and_b32 s9, s8, 0xff
	s_mov_b64 s[44:45], -1
	s_cmp_lg_u32 s9, 0
	s_mov_b64 s[48:49], -1
	s_sleep 0
	s_cbranch_scc1 .LBB0_710
	v_readlane_b32 s12, v254, 11
	v_readlane_b32 s13, v254, 12
	s_nop 4
	global_load_dword v2, v1, s[12:13] sc1
	s_waitcnt vmcnt(0)
	v_cmp_eq_u32_e32 vcc, 0, v2
	s_cbranch_vccnz .LBB0_712
	s_mov_b64 s[48:49], 0
	s_mov_b64 s[46:47], -1

; __device__ __forceinline__ unsigned xb_ld(unsigned* p)              { return __hip_atomic_load(p, __ATOMIC_RELAXED, __HIP_MEMORY_SCOPE_AGENT); }
; __device__ __forceinline__ void xcd_barrier_complete(unsigned* bar, unsigned x, unsigned& nloc, unsigned& nx) {
;     const unsigned G = gridDim.x * gridDim.y * gridDim.z;
;     unsigned sum, cnt, mine, sp = 0u;
;     for (;;) {
;         sum = 0u; cnt = 0u; mine = 0u;
; #pragma unroll
;         for (unsigned j = 0; j < 16; ++j) { const unsigned c = xb_ld(&bar[XB_XCNT(j)]); sum += c; cnt += (c > 0u) ? 1u : 0u; mine = (j == x) ? c : mine; }
;         if (sum == G) break;
;         __builtin_amdgcn_s_sleep(1);
;         if ((++sp & 255u) == 0u) { if (xb_ld(&bar[XB_TMO])) break; if (sp > XB_SPIN_CAP) { atomicAdd(&bar[XB_TMO], 1u); break; } }
;     }
.LBB0_753:
	v_readlane_b32 s4, v254, 13
	v_readlane_b32 s5, v254, 14
	s_mov_b64 s[6:7], -1
	s_nop 3
	global_load_dword v0, v1, s[4:5] sc1
	v_readlane_b32 s4, v254, 15
	v_readlane_b32 s5, v254, 16
	s_nop 4
	global_load_dword v2, v1, s[4:5] sc1
	v_readlane_b32 s4, v254, 17
	v_readlane_b32 s5, v254, 18
	s_waitcnt vmcnt(0)
	v_add_u32_e32 v17, v2, v0
	s_nop 2
	global_load_dword v3, v1, s[4:5] sc1
	v_readlane_b32 s4, v254, 19
	v_readlane_b32 s5, v254, 20
	s_waitcnt vmcnt(0)
	v_add_u32_e32 v17, v17, v3
	s_nop 2
	global_load_dword v4, v1, s[4:5] sc1
	v_readlane_b32 s4, v254, 21
	v_readlane_b32 s5, v254, 22
	s_waitcnt vmcnt(0)
	v_add_u32_e32 v17, v17, v4
	s_nop 2
	global_load_dword v5, v1, s[4:5] sc1
	v_readlane_b32 s4, v254, 23
	v_readlane_b32 s5, v254, 24
	s_waitcnt vmcnt(0)
	v_add_u32_e32 v17, v17, v5
	s_nop 2
	global_load_dword v6, v1, s[4:5] sc1
	v_readlane_b32 s4, v254, 25
	v_readlane_b32 s5, v254, 26
	s_waitcnt vmcnt(0)
	v_add_u32_e32 v17, v17, v6
	s_nop 2
	global_load_dword v7, v1, s[4:5] sc1
	v_readlane_b32 s4, v254, 27
	v_readlane_b32 s5, v254, 28
	s_waitcnt vmcnt(0)
	v_add_u32_e32 v17, v17, v7
	s_nop 2
	global_load_dword v8, v1, s[4:5] sc1
	v_readlane_b32 s4, v254, 29
	v_readlane_b32 s5, v254, 30
	s_waitcnt vmcnt(0)
	v_add_u32_e32 v17, v17, v8
	s_nop 2
	global_load_dword v9, v1, s[4:5] sc1
	v_readlane_b32 s4, v254, 31
	v_readlane_b32 s5, v254, 32
	s_waitcnt vmcnt(0)
	v_add_u32_e32 v17, v17, v9
	s_nop 2
	global_load_dword v10, v1, s[4:5] sc1
	v_readlane_b32 s4, v254, 33
	v_readlane_b32 s5, v254, 34
	s_waitcnt vmcnt(0)
	v_add_u32_e32 v17, v17, v10
	s_nop 2
	global_load_dword v11, v1, s[4:5] sc1
	v_readlane_b32 s4, v254, 35
	v_readlane_b32 s5, v254, 36
	s_waitcnt vmcnt(0)
	v_add_u32_e32 v17, v17, v11
	s_nop 2
	global_load_dword v12, v1, s[4:5] sc1
	v_readlane_b32 s4, v254, 37
	v_readlane_b32 s5, v254, 38
	s_waitcnt vmcnt(0)
	v_add_u32_e32 v17, v17, v12
	s_nop 2
	global_load_dword v13, v1, s[4:5] sc1
	v_readlane_b32 s4, v254, 39
	v_readlane_b32 s5, v254, 40
	s_waitcnt vmcnt(0)
	v_add_u32_e32 v17, v17, v13
	s_nop 2
	global_load_dword v14, v1, s[4:5] sc1
	v_readlane_b32 s4, v254, 41
	v_readlane_b32 s5, v254, 42
	s_waitcnt vmcnt(0)
	v_add_u32_e32 v17, v17, v14
	s_nop 2
	global_load_dword v15, v1, s[4:5] sc1
	v_readlane_b32 s4, v254, 43
	v_readlane_b32 s5, v254, 44
	s_waitcnt vmcnt(0)
	v_add_u32_e32 v17, v17, v15
	s_nop 2
	global_load_dword v16, v1, s[4:5] sc1
	s_mov_b64 s[4:5], -1
	s_waitcnt vmcnt(0)
	v_add_u32_e32 v17, v17, v16
	v_cmp_eq_u32_e32 vcc, s8, v17
	s_cbranch_vccnz .LBB0_752
	s_and_b32 s4, s9, 0xff
	s_cmp_eq_u32 s4, 0
	s_mov_b64 s[4:5], -1
	s_mov_b64 s[40:41], -1
	s_sleep 0
	s_cbranch_scc0 .LBB0_757
	v_readlane_b32 s4, v254, 11
	v_readlane_b32 s5, v254, 12
	s_nop 4
	global_load_dword v17, v1, s[4:5] sc1
	s_waitcnt vmcnt(0)
	v_cmp_eq_u32_e32 vcc, 0, v17
	s_cbranch_vccnz .LBB0_759
	s_mov_b64 s[40:41], 0
	s_mov_b64 s[4:5], -1
